# v106: v103 + workspace-pointer scalar load hoisted above the seam head waits/barrier
# speedup vs baseline: 1.0004x; 1.0004x over previous
.LBB0_119:
	s_cmp_gt_i32 s41, 1
	s_cselect_b64 s[6:7], -1, 0
	s_and_b64 s[8:9], s[22:23], s[6:7]
	s_andn2_b64 vcc, exec, s[8:9]
	s_cbranch_vccnz .LBB0_173
	s_load_dwordx2 s[10:11], s[0:1], 0x68
	s_getreg_b32 s3, hwreg(HW_REG_XCC_ID, 0, 4)
	s_waitcnt vmcnt(0)
	s_barrier
	s_and_saveexec_b64 s[8:9], s[4:5]
	s_cbranch_execz .LBB0_172
	s_add_i32 s12, 0, 0x26c00
	v_mov_b32_e32 v0, s12
	s_nop 0
	s_waitcnt vmcnt(0) expcnt(0) lgkmcnt(0)
	ds_read_b32 v2, v0
	s_add_i32 s12, 0, 0x26c04
	v_mov_b32_e32 v0, s12
	ds_read_b32 v0, v0
	s_and_b32 s3, s3, 15
	s_waitcnt lgkmcnt(1)
	v_cmp_ne_u32_e32 vcc, 0, v2
	s_cbranch_vccnz .LBB0_136
	s_load_dwordx2 s[16:17], s[0:1], 0x78
	s_load_dword s15, s[0:1], 0x80
	s_add_u32 s12, s10, 0x60200
	s_addc_u32 s13, s11, 0
	s_add_u32 s14, s10, 0x60400
	s_waitcnt lgkmcnt(0)
	s_mul_i32 s33, s17, s16
	s_mul_i32 s33, s33, s15
	s_addc_u32 s15, s11, 0
	s_add_u32 s16, s10, 0x60500
	s_addc_u32 s17, s11, 0
	s_add_u32 s18, s10, 0x60600
	s_addc_u32 s19, s11, 0
	s_add_u32 s20, s10, 0x60700
	s_addc_u32 s21, s11, 0
	s_add_u32 s22, s10, 0x60800
	s_addc_u32 s23, s11, 0
	s_add_u32 s24, s10, 0x60900
	s_addc_u32 s25, s11, 0
	s_add_u32 s26, s10, 0x60a00
	s_addc_u32 s27, s11, 0
	s_add_u32 s28, s10, 0x60b00
	s_addc_u32 s29, s11, 0
	s_add_u32 s30, s10, 0x60c00
	s_addc_u32 s31, s11, 0
	s_add_u32 s34, s10, 0x60d00
	s_addc_u32 s35, s11, 0
	s_add_u32 s36, s10, 0x60e00
	s_addc_u32 s37, s11, 0
	s_add_u32 s38, s10, 0x60f00
	s_addc_u32 s39, s11, 0
	s_add_u32 s42, s10, 0x61000
	s_addc_u32 s43, s11, 0
	s_add_u32 s44, s10, 0x61100
	s_addc_u32 s45, s11, 0
	s_add_u32 s46, s10, 0x61200
	s_addc_u32 s47, s11, 0
	s_add_u32 s48, s10, 0x61300
	s_addc_u32 s49, s11, 0
	s_mov_b32 s56, 1
	v_mov_b32_e32 v16, 0
	s_branch .LBB0_124

.LBB0_217:
	s_cmp_gt_i32 s41, 2
	s_cselect_b64 s[6:7], -1, 0
	s_and_b64 s[8:9], s[12:13], s[6:7]
	s_andn2_b64 vcc, exec, s[8:9]
	s_cbranch_vccnz .LBB0_271
	s_load_dwordx2 s[10:11], s[0:1], 0x68
	s_getreg_b32 s3, hwreg(HW_REG_XCC_ID, 0, 4)
	s_waitcnt vmcnt(0)
	s_waitcnt vmcnt(0)
	s_barrier
	s_and_saveexec_b64 s[8:9], s[4:5]
	s_cbranch_execz .LBB0_270
	s_add_i32 s12, 0, 0x26c00
	v_mov_b32_e32 v0, s12
	s_nop 0
	s_waitcnt vmcnt(0) expcnt(0) lgkmcnt(0)
	ds_read_b32 v2, v0
	s_add_i32 s12, 0, 0x26c04
	v_mov_b32_e32 v0, s12
	ds_read_b32 v0, v0
	s_and_b32 s3, s3, 15
	s_waitcnt lgkmcnt(1)
	v_cmp_ne_u32_e32 vcc, 0, v2
	s_cbranch_vccnz .LBB0_234
	s_load_dwordx2 s[16:17], s[0:1], 0x78
	s_load_dword s15, s[0:1], 0x80
	s_add_u32 s12, s10, 0x60200
	s_addc_u32 s13, s11, 0
	s_add_u32 s14, s10, 0x60400
	s_waitcnt lgkmcnt(0)
	s_mul_i32 s33, s17, s16
	s_mul_i32 s33, s33, s15
	s_addc_u32 s15, s11, 0
	s_add_u32 s16, s10, 0x60500
	s_addc_u32 s17, s11, 0
	s_add_u32 s18, s10, 0x60600
	s_addc_u32 s19, s11, 0
	s_add_u32 s20, s10, 0x60700
	s_addc_u32 s21, s11, 0
	s_add_u32 s22, s10, 0x60800
	s_addc_u32 s23, s11, 0
	s_add_u32 s24, s10, 0x60900
	s_addc_u32 s25, s11, 0
	s_add_u32 s26, s10, 0x60a00
	s_addc_u32 s27, s11, 0
	s_add_u32 s28, s10, 0x60b00
	s_addc_u32 s29, s11, 0
	s_add_u32 s30, s10, 0x60c00
	s_addc_u32 s31, s11, 0
	s_add_u32 s34, s10, 0x60d00
	s_addc_u32 s35, s11, 0
	s_add_u32 s36, s10, 0x60e00
	s_addc_u32 s37, s11, 0
	s_add_u32 s38, s10, 0x60f00
	s_addc_u32 s39, s11, 0
	s_add_u32 s42, s10, 0x61000
	s_addc_u32 s43, s11, 0
	s_add_u32 s44, s10, 0x61100
	s_addc_u32 s45, s11, 0
	s_add_u32 s46, s10, 0x61200
	s_addc_u32 s47, s11, 0
	s_add_u32 s48, s10, 0x61300
	s_addc_u32 s49, s11, 0
	s_mov_b32 s56, 1
	v_mov_b32_e32 v16, 0
	s_branch .LBB0_222

.LBB0_285:
	s_cmp_gt_i32 s41, 3
	s_cselect_b64 s[6:7], -1, 0
	s_and_b64 s[8:9], s[42:43], s[6:7]
	s_andn2_b64 vcc, exec, s[8:9]
	s_cbranch_vccnz .LBB0_339
	s_load_dwordx2 s[10:11], s[0:1], 0x68
	s_getreg_b32 s3, hwreg(HW_REG_XCC_ID, 0, 4)
	s_waitcnt vmcnt(0)
	s_waitcnt vmcnt(0)
	s_barrier
	s_and_saveexec_b64 s[8:9], s[4:5]
	s_cbranch_execz .LBB0_338
	s_add_i32 s12, 0, 0x26c00
	v_mov_b32_e32 v0, s12
	s_nop 0
	s_waitcnt vmcnt(0) expcnt(0) lgkmcnt(0)
	ds_read_b32 v2, v0
	s_add_i32 s12, 0, 0x26c04
	v_mov_b32_e32 v0, s12
	ds_read_b32 v0, v0
	s_and_b32 s3, s3, 15
	s_waitcnt lgkmcnt(1)
	v_cmp_ne_u32_e32 vcc, 0, v2
	s_cbranch_vccnz .LBB0_302
	s_load_dwordx2 s[16:17], s[0:1], 0x78
	s_load_dword s15, s[0:1], 0x80
	s_add_u32 s12, s10, 0x60200
	s_addc_u32 s13, s11, 0
	s_add_u32 s14, s10, 0x60400
	s_waitcnt lgkmcnt(0)
	s_mul_i32 s33, s17, s16
	s_mul_i32 s33, s33, s15
	s_addc_u32 s15, s11, 0
	s_add_u32 s16, s10, 0x60500
	s_addc_u32 s17, s11, 0
	s_add_u32 s18, s10, 0x60600
	s_addc_u32 s19, s11, 0
	s_add_u32 s20, s10, 0x60700
	s_addc_u32 s21, s11, 0
	s_add_u32 s22, s10, 0x60800
	s_addc_u32 s23, s11, 0
	s_add_u32 s24, s10, 0x60900
	s_addc_u32 s25, s11, 0
	s_add_u32 s26, s10, 0x60a00
	s_addc_u32 s27, s11, 0
	s_add_u32 s28, s10, 0x60b00
	s_addc_u32 s29, s11, 0
	s_add_u32 s30, s10, 0x60c00
	s_addc_u32 s31, s11, 0
	s_add_u32 s34, s10, 0x60d00
	s_addc_u32 s35, s11, 0
	s_add_u32 s36, s10, 0x60e00
	s_addc_u32 s37, s11, 0
	s_add_u32 s38, s10, 0x60f00
	s_addc_u32 s39, s11, 0
	s_add_u32 s42, s10, 0x61000
	s_addc_u32 s43, s11, 0
	s_add_u32 s44, s10, 0x61100
	s_addc_u32 s45, s11, 0
	s_add_u32 s46, s10, 0x61200
	s_addc_u32 s47, s11, 0
	s_add_u32 s48, s10, 0x61300
	s_addc_u32 s49, s11, 0
	s_mov_b32 s56, 1
	v_mov_b32_e32 v16, 0
	s_branch .LBB0_290

.LBB0_352:
	s_cmp_gt_i32 s41, 4
	s_cselect_b64 s[6:7], -1, 0
	s_and_b64 s[8:9], s[22:23], s[6:7]
	s_andn2_b64 vcc, exec, s[8:9]
	s_cbranch_vccnz .LBB0_406
	s_load_dwordx2 s[10:11], s[0:1], 0x68
	s_getreg_b32 s3, hwreg(HW_REG_XCC_ID, 0, 4)
	s_waitcnt vmcnt(0)
	s_waitcnt vmcnt(0) lgkmcnt(0)
	s_barrier
	s_and_saveexec_b64 s[8:9], s[4:5]
	s_cbranch_execz .LBB0_405
	s_add_i32 s12, 0, 0x26c00
	v_mov_b32_e32 v0, s12
	s_nop 0
	s_waitcnt vmcnt(0) expcnt(0) lgkmcnt(0)
	ds_read_b32 v2, v0
	s_add_i32 s12, 0, 0x26c04
	v_mov_b32_e32 v0, s12
	ds_read_b32 v0, v0
	s_and_b32 s3, s3, 15
	s_waitcnt lgkmcnt(1)
	v_cmp_ne_u32_e32 vcc, 0, v2
	s_cbranch_vccnz .LBB0_369
	s_load_dwordx2 s[16:17], s[0:1], 0x78
	s_load_dword s15, s[0:1], 0x80
	s_add_u32 s12, s10, 0x60200
	s_addc_u32 s13, s11, 0
	s_add_u32 s14, s10, 0x60400
	s_waitcnt lgkmcnt(0)
	s_mul_i32 s33, s17, s16
	s_mul_i32 s33, s33, s15
	s_addc_u32 s15, s11, 0
	s_add_u32 s16, s10, 0x60500
	s_addc_u32 s17, s11, 0
	s_add_u32 s18, s10, 0x60600
	s_addc_u32 s19, s11, 0
	s_add_u32 s20, s10, 0x60700
	s_addc_u32 s21, s11, 0
	s_add_u32 s22, s10, 0x60800
	s_addc_u32 s23, s11, 0
	s_add_u32 s24, s10, 0x60900
	s_addc_u32 s25, s11, 0
	s_add_u32 s26, s10, 0x60a00
	s_addc_u32 s27, s11, 0
	s_add_u32 s28, s10, 0x60b00
	s_addc_u32 s29, s11, 0
	s_add_u32 s30, s10, 0x60c00
	s_addc_u32 s31, s11, 0
	s_add_u32 s34, s10, 0x60d00
	s_addc_u32 s35, s11, 0
	s_add_u32 s36, s10, 0x60e00
	s_addc_u32 s37, s11, 0
	s_add_u32 s38, s10, 0x60f00
	s_addc_u32 s39, s11, 0
	s_add_u32 s42, s10, 0x61000
	s_addc_u32 s43, s11, 0
	s_add_u32 s44, s10, 0x61100
	s_addc_u32 s45, s11, 0
	s_add_u32 s46, s10, 0x61200
	s_addc_u32 s47, s11, 0
	s_add_u32 s48, s10, 0x61300
	s_addc_u32 s49, s11, 0
	s_mov_b32 s56, 1
	v_mov_b32_e32 v16, 0
	s_branch .LBB0_357

.LBB0_411:
	s_cmp_gt_i32 s41, 5
	s_cselect_b64 s[6:7], -1, 0
	s_and_b64 s[8:9], s[12:13], s[6:7]
	s_andn2_b64 vcc, exec, s[8:9]
	s_cbranch_vccnz .LBB0_465
	s_load_dwordx2 s[10:11], s[0:1], 0x68
	s_getreg_b32 s3, hwreg(HW_REG_XCC_ID, 0, 4)
	s_waitcnt vmcnt(0)
	s_waitcnt vmcnt(0) lgkmcnt(0)
	s_barrier
	s_and_saveexec_b64 s[8:9], s[4:5]
	s_cbranch_execz .LBB0_464
	s_waitcnt lgkmcnt(0)
	s_mov_b64 s[4:5], s[10:11]
	s_add_i32 s10, 0, 0x26c00
	v_mov_b32_e32 v0, s10
	s_waitcnt vmcnt(0) expcnt(0) lgkmcnt(0)
	ds_read_b32 v2, v0
	s_add_i32 s10, 0, 0x26c04
	v_mov_b32_e32 v0, s10
	ds_read_b32 v0, v0
	s_and_b32 s3, s3, 15
	s_waitcnt lgkmcnt(1)
	v_cmp_ne_u32_e32 vcc, 0, v2
	s_cbranch_vccnz .LBB0_428
	s_load_dwordx2 s[14:15], s[0:1], 0x78
	s_load_dword s13, s[0:1], 0x80
	s_add_u32 s10, s4, 0x60200
	s_addc_u32 s11, s5, 0
	s_add_u32 s12, s4, 0x60400
	s_waitcnt lgkmcnt(0)
	s_mul_i32 s33, s15, s14
	s_mul_i32 s33, s33, s13
	s_addc_u32 s13, s5, 0
	s_add_u32 s14, s4, 0x60500
	s_addc_u32 s15, s5, 0
	s_add_u32 s16, s4, 0x60600
	s_addc_u32 s17, s5, 0
	s_add_u32 s18, s4, 0x60700
	s_addc_u32 s19, s5, 0
	s_add_u32 s20, s4, 0x60800
	s_addc_u32 s21, s5, 0
	s_add_u32 s22, s4, 0x60900
	s_addc_u32 s23, s5, 0
	s_add_u32 s24, s4, 0x60a00
	s_addc_u32 s25, s5, 0
	s_add_u32 s26, s4, 0x60b00
	s_addc_u32 s27, s5, 0
	s_add_u32 s28, s4, 0x60c00
	s_addc_u32 s29, s5, 0
	s_add_u32 s30, s4, 0x60d00
	s_addc_u32 s31, s5, 0
	s_add_u32 s34, s4, 0x60e00
	s_addc_u32 s35, s5, 0
	s_add_u32 s36, s4, 0x60f00
	s_addc_u32 s37, s5, 0
	s_add_u32 s38, s4, 0x61000
	s_addc_u32 s39, s5, 0
	s_add_u32 s42, s4, 0x61100
	s_addc_u32 s43, s5, 0
	s_add_u32 s44, s4, 0x61200
	s_addc_u32 s45, s5, 0
	s_add_u32 s46, s4, 0x61300
	s_addc_u32 s47, s5, 0
	s_mov_b32 s41, 1
	v_mov_b32_e32 v16, 0
	s_branch .LBB0_416
